# v27 + GEMM mainloop: removed the redundant post-barrier lgkmcnt(0) and merged the two pre-barrier waits into one s_waitcnt
# speedup vs baseline: 1.0056x; 1.0016x over previous
; #define PG8_STAGE(bufoff, gbase, voff) do { _Pragma("unroll") for (int _i = 0; _i < 2; ++_i) \
;         __builtin_amdgcn_global_load_lds((const unsigned*)((const char*)(gbase) + (voff)[_i]), (PG8_LAS unsigned*)(lds + (bufoff) + ldsw + _i * 8192), 16, 0, 0); } while (0)
; #define PG8_LDA(dst, b, h) do { _Pragma("unroll") for (int m = 0; m < 4; ++m) _Pragma("unroll") for (int k = 0; k < 2; ++k) dst[m][k] = *(const PG8_LAS bf16x8*)(lds + PG8_SA(b, h) + aoff + m * 2048 + k * 1024); } while (0)
; #define PG8_LDB(dst, b, h) do { _Pragma("unroll") for (int n = 0; n < 2; ++n) _Pragma("unroll") for (int k = 0; k < 2; ++k) dst[n][k] = *(const PG8_LAS bf16x8*)(lds + PG8_SB(b, h) + boff + n * 2048 + k * 1024); } while (0)
; #define PG8_MMA(ai, bj, At, Bt) do { __builtin_amdgcn_s_setprio(1); _Pragma("unroll") for (int m = 0; m < 4; ++m) _Pragma("unroll") for (int n = 0; n < 2; ++n) _Pragma("unroll") for (int k = 0; k < 2; ++k) \
;         acc[ai][bj][m][n] = __builtin_amdgcn_mfma_f32_16x16x32_bf16(Bt[n][k], At[m][k], acc[ai][bj][m][n], 0, 0, 0); __builtin_amdgcn_s_setprio(0); } while (0)
; #define PG8_WAIT_V(n) asm volatile("s_waitcnt vmcnt(" #n ")" ::: "memory")
; #define PG8_BAR __builtin_amdgcn_s_barrier()
; template <class Epi, class Sched, bool ALIGN_EPI = false, bool SP2 = false>
; __device__ __forceinline__ void gemm_phase(PG8_LAS unsigned char* lds, const Gemm g, const Sched& S, const Epi& E) {
;     ...
;         for (int t = 0; t < nt; t += 2) {
;             const bool last = (t == nt - 2);
;             const char* a1 = cA + (size_t)(t + 1) * kstep;
;             const char* a2 = last ? nA : cA + (size_t)(t + 2) * kstep; const char* b2 = last ? nB : cB + (size_t)(t + 2) * kstep;
;             const char* a3 = a2 + kstep; const char* b3 = b2 + kstep;
;             if (last && has_next) S.a_ready(nxt);
;             if constexpr (SP2) {
;             PG8_LDB(B0, 0, 0); PG8_LDB(B1, 0, 1); PG8_SCHED; PG8_LDA(At, 0, 0); PG8_STAGE(PG8_SA(1, 1), a1 + hstepA, voffA);
;             PG8_WAIT_V(8); PG8_WAIT_L(0); PG8_BAR; PG8_MMA(0, 0, At, B0); PG8_MMA(0, 1, At, B1); PG8_BAR; PG8_SCHED;
;             PG8_LDA(At, 0, 1); PG8_STAGE(PG8_SB(0, 0), b2, voffB); PG8_STAGE(PG8_SB(0, 1), b2 + hstepB, voffB); PG8_STAGE(PG8_SA(0, 0), a2, voffA);
;             PG8_WAIT_V(8); PG8_WAIT_L(0); PG8_BAR; PG8_MMA(1, 0, At, B0); PG8_MMA(1, 1, At, B1); PG8_BAR; PG8_SCHED;
.LBB0_380:
	s_add_i32 s84, s40, 2
	s_add_u32 s81, s78, 0x80
	s_addc_u32 s41, s79, 0
	s_add_i32 s85, 0, 0x10000
	s_cmp_eq_u32 s34, s40
	s_cselect_b32 s41, s45, s41
	s_cselect_b32 s40, s44, s81
	s_cselect_b32 s89, s75, s83
	s_cselect_b32 s88, s74, s77
	s_add_i32 s81, 0, 0x14000
	v_add_u32_e32 v140, s85, v249
	v_add_u32_e32 v156, s81, v249
	ds_read_b128 v[124:127], v140
	ds_read_b128 v[128:131], v140 offset:1024
	ds_read_b128 v[132:135], v140 offset:2048
	ds_read_b128 v[140:143], v140 offset:3072
	ds_read_b128 v[144:147], v156
	ds_read_b128 v[148:151], v156 offset:1024
	ds_read_b128 v[152:155], v156 offset:2048
	ds_read_b128 v[156:159], v156 offset:3072
	v_lshl_add_u64 v[208:209], s[78:79], 0, v[206:207]
	s_add_i32 m0, s12, 0xc000
	ds_read_b128 v[160:163], v251
	ds_read_b128 v[164:167], v251 offset:1024
	ds_read_b128 v[168:171], v251 offset:2048
	ds_read_b128 v[172:175], v251 offset:3072
	ds_read_b128 v[176:179], v251 offset:4096
	ds_read_b128 v[180:183], v251 offset:5120
	ds_read_b128 v[184:187], v251 offset:6144
	ds_read_b128 v[188:191], v251 offset:7168
	global_load_lds_dwordx4 v[208:209], off
	v_lshl_add_u64 v[208:209], s[78:79], 0, v[204:205]
	s_add_i32 m0, s12, 0xe000
	s_nop 0
	global_load_lds_dwordx4 v[208:209], off
	s_waitcnt vmcnt(8) lgkmcnt(0)
	s_barrier
	s_setprio 1
	v_mfma_f32_16x16x32_bf16 v[136:139], v[124:127], v[160:163], v[136:139]
	v_mfma_f32_16x16x32_bf16 v[120:123], v[132:135], v[160:163], v[120:123]
	v_mfma_f32_16x16x32_bf16 v[108:111], v[124:127], v[168:171], v[108:111]
	v_mfma_f32_16x16x32_bf16 v[104:107], v[132:135], v[168:171], v[104:107]
	v_mfma_f32_16x16x32_bf16 v[92:95], v[124:127], v[176:179], v[92:95]
	v_mfma_f32_16x16x32_bf16 v[88:91], v[132:135], v[176:179], v[88:91]
	v_mfma_f32_16x16x32_bf16 v[76:79], v[124:127], v[184:187], v[76:79]
	v_mfma_f32_16x16x32_bf16 v[72:75], v[132:135], v[184:187], v[72:75]
	v_mfma_f32_16x16x32_bf16 v[136:139], v[128:131], v[164:167], v[136:139]
	v_mfma_f32_16x16x32_bf16 v[120:123], v[140:143], v[164:167], v[120:123]
	v_mfma_f32_16x16x32_bf16 v[108:111], v[128:131], v[172:175], v[108:111]
	v_mfma_f32_16x16x32_bf16 v[104:107], v[140:143], v[172:175], v[104:107]
	v_mfma_f32_16x16x32_bf16 v[92:95], v[128:131], v[180:183], v[92:95]
	v_mfma_f32_16x16x32_bf16 v[88:91], v[140:143], v[180:183], v[88:91]
	v_mfma_f32_16x16x32_bf16 v[76:79], v[128:131], v[188:191], v[76:79]
	v_mfma_f32_16x16x32_bf16 v[72:75], v[140:143], v[188:191], v[72:75]
	v_mfma_f32_16x16x32_bf16 v[116:119], v[144:147], v[160:163], v[116:119]
	v_mfma_f32_16x16x32_bf16 v[112:115], v[152:155], v[160:163], v[112:115]
	v_mfma_f32_16x16x32_bf16 v[100:103], v[144:147], v[168:171], v[100:103]
	v_mfma_f32_16x16x32_bf16 v[96:99], v[152:155], v[168:171], v[96:99]
	v_mfma_f32_16x16x32_bf16 v[84:87], v[144:147], v[176:179], v[84:87]
	v_mfma_f32_16x16x32_bf16 v[80:83], v[152:155], v[176:179], v[80:83]
	v_mfma_f32_16x16x32_bf16 v[68:71], v[144:147], v[184:187], v[68:71]
	v_mfma_f32_16x16x32_bf16 v[64:67], v[152:155], v[184:187], v[64:67]
	v_mfma_f32_16x16x32_bf16 v[116:119], v[148:151], v[164:167], v[116:119]
	v_mfma_f32_16x16x32_bf16 v[112:115], v[156:159], v[164:167], v[112:115]
	v_mfma_f32_16x16x32_bf16 v[100:103], v[148:151], v[172:175], v[100:103]
	v_mfma_f32_16x16x32_bf16 v[96:99], v[156:159], v[172:175], v[96:99]
	v_mfma_f32_16x16x32_bf16 v[84:87], v[148:151], v[180:183], v[84:87]
	v_mfma_f32_16x16x32_bf16 v[80:83], v[156:159], v[180:183], v[80:83]
	v_mfma_f32_16x16x32_bf16 v[68:71], v[148:151], v[188:191], v[68:71]
	v_mfma_f32_16x16x32_bf16 v[64:67], v[156:159], v[188:191], v[64:67]
	s_setprio 0
	s_barrier
	s_add_i32 s85, s85, s11
	v_lshl_add_u64 v[208:209], s[88:89], 0, v[194:195]
	s_mov_b32 m0, s85
	ds_read_b128 v[160:163], v251 offset:16384
	ds_read_b128 v[164:167], v251 offset:17408
	ds_read_b128 v[168:171], v251 offset:18432
	ds_read_b128 v[172:175], v251 offset:19456
	ds_read_b128 v[176:179], v251 offset:20480
	ds_read_b128 v[180:183], v251 offset:21504
	ds_read_b128 v[184:187], v251 offset:22528
	ds_read_b128 v[188:191], v251 offset:23552
	global_load_lds_dwordx4 v[208:209], off
	s_add_i32 m0, s85, 0x2000
	v_lshl_add_u64 v[210:211], s[88:89], 0, v[202:203]
	s_add_u32 s88, s88, s24
	s_addc_u32 s89, s89, 0
	s_add_i32 s81, s81, s11
	global_load_lds_dwordx4 v[210:211], off
	v_lshl_add_u64 v[212:213], s[88:89], 0, v[194:195]
	s_mov_b32 m0, s81
	v_lshl_add_u64 v[214:215], s[88:89], 0, v[202:203]
	global_load_lds_dwordx4 v[212:213], off
	s_add_i32 m0, s81, 0x2000
	v_lshl_add_u64 v[216:217], s[40:41], 0, v[198:199]
	global_load_lds_dwordx4 v[214:215], off
	s_mov_b32 m0, s12
	v_lshl_add_u64 v[218:219], s[40:41], 0, v[200:201]
	global_load_lds_dwordx4 v[216:217], off
	s_mov_b32 m0, s13
	s_nop 0
	global_load_lds_dwordx4 v[218:219], off
	s_waitcnt vmcnt(8) lgkmcnt(0)
	s_barrier
; #define PG8_STAGE(bufoff, gbase, voff) do { _Pragma("unroll") for (int _i = 0; _i < 2; ++_i) \
;         __builtin_amdgcn_global_load_lds((const unsigned*)((const char*)(gbase) + (voff)[_i]), (PG8_LAS unsigned*)(lds + (bufoff) + ldsw + _i * 8192), 16, 0, 0); } while (0)
; #define PG8_LDA(dst, b, h) do { _Pragma("unroll") for (int m = 0; m < 4; ++m) _Pragma("unroll") for (int k = 0; k < 2; ++k) dst[m][k] = *(const PG8_LAS bf16x8*)(lds + PG8_SA(b, h) + aoff + m * 2048 + k * 1024); } while (0)
; #define PG8_LDB(dst, b, h) do { _Pragma("unroll") for (int n = 0; n < 2; ++n) _Pragma("unroll") for (int k = 0; k < 2; ++k) dst[n][k] = *(const PG8_LAS bf16x8*)(lds + PG8_SB(b, h) + boff + n * 2048 + k * 1024); } while (0)
; #define PG8_MMA(ai, bj, At, Bt) do { __builtin_amdgcn_s_setprio(1); _Pragma("unroll") for (int m = 0; m < 4; ++m) _Pragma("unroll") for (int n = 0; n < 2; ++n) _Pragma("unroll") for (int k = 0; k < 2; ++k) \
;         acc[ai][bj][m][n] = __builtin_amdgcn_mfma_f32_16x16x32_bf16(Bt[n][k], At[m][k], acc[ai][bj][m][n], 0, 0, 0); __builtin_amdgcn_s_setprio(0); } while (0)
; #define PG8_WAIT_V(n) asm volatile("s_waitcnt vmcnt(" #n ")" ::: "memory")
; #define PG8_WAIT_L(n) asm volatile("s_waitcnt lgkmcnt(" #n ")" ::: "memory")
; #define PG8_BAR __builtin_amdgcn_s_barrier()
; #define PG8_SCHED __builtin_amdgcn_sched_barrier(0)
; template <class Epi, class Sched, bool ALIGN_EPI = false, bool SP2 = false>
; __device__ __forceinline__ void gemm_phase(PG8_LAS unsigned char* lds, const Gemm g, const Sched& S, const Epi& E) {
;     ...
;             PG8_WAIT_V(8); PG8_WAIT_L(0); PG8_BAR; PG8_MMA(1, 0, At, B0); PG8_MMA(1, 1, At, B1); PG8_BAR; PG8_SCHED;
;             PG8_LDB(B0, 1, 0); PG8_LDB(B1, 1, 1); PG8_SCHED; PG8_LDA(At, 1, 0); PG8_STAGE(PG8_SA(0, 1), a2 + hstepA, voffA);
;             PG8_WAIT_V(8); PG8_WAIT_L(0); PG8_BAR; PG8_MMA(0, 0, At, B0); PG8_MMA(0, 1, At, B1); PG8_BAR; PG8_SCHED;
	s_setprio 1
	v_mfma_f32_16x16x32_bf16 v[60:63], v[124:127], v[160:163], v[60:63]
	v_mfma_f32_16x16x32_bf16 v[56:59], v[132:135], v[160:163], v[56:59]
	v_mfma_f32_16x16x32_bf16 v[44:47], v[124:127], v[168:171], v[44:47]
	v_mfma_f32_16x16x32_bf16 v[40:43], v[132:135], v[168:171], v[40:43]
	v_mfma_f32_16x16x32_bf16 v[28:31], v[124:127], v[176:179], v[28:31]
	v_mfma_f32_16x16x32_bf16 v[24:27], v[132:135], v[176:179], v[24:27]
	v_mfma_f32_16x16x32_bf16 v[12:15], v[124:127], v[184:187], v[12:15]
	v_mfma_f32_16x16x32_bf16 v[8:11], v[132:135], v[184:187], v[8:11]
	v_mfma_f32_16x16x32_bf16 v[60:63], v[128:131], v[164:167], v[60:63]
	v_mfma_f32_16x16x32_bf16 v[56:59], v[140:143], v[164:167], v[56:59]
	v_mfma_f32_16x16x32_bf16 v[44:47], v[128:131], v[172:175], v[44:47]
	v_mfma_f32_16x16x32_bf16 v[40:43], v[140:143], v[172:175], v[40:43]
	v_mfma_f32_16x16x32_bf16 v[28:31], v[128:131], v[180:183], v[28:31]
	v_mfma_f32_16x16x32_bf16 v[24:27], v[140:143], v[180:183], v[24:27]
	v_mfma_f32_16x16x32_bf16 v[12:15], v[128:131], v[188:191], v[12:15]
	v_mfma_f32_16x16x32_bf16 v[8:11], v[140:143], v[188:191], v[8:11]
	v_mfma_f32_16x16x32_bf16 v[52:55], v[144:147], v[160:163], v[52:55]
	v_mfma_f32_16x16x32_bf16 v[48:51], v[152:155], v[160:163], v[48:51]
	v_mfma_f32_16x16x32_bf16 v[36:39], v[144:147], v[168:171], v[36:39]
	v_mfma_f32_16x16x32_bf16 v[32:35], v[152:155], v[168:171], v[32:35]
	v_mfma_f32_16x16x32_bf16 v[20:23], v[144:147], v[176:179], v[20:23]
	v_mfma_f32_16x16x32_bf16 v[16:19], v[152:155], v[176:179], v[16:19]
	v_mfma_f32_16x16x32_bf16 v[4:7], v[144:147], v[184:187], v[4:7]
	v_mfma_f32_16x16x32_bf16 v[0:3], v[152:155], v[184:187], v[0:3]
	v_mfma_f32_16x16x32_bf16 v[52:55], v[148:151], v[164:167], v[52:55]
	v_mfma_f32_16x16x32_bf16 v[48:51], v[156:159], v[164:167], v[48:51]
	v_mfma_f32_16x16x32_bf16 v[36:39], v[148:151], v[172:175], v[36:39]
	v_mfma_f32_16x16x32_bf16 v[32:35], v[156:159], v[172:175], v[32:35]
	v_mfma_f32_16x16x32_bf16 v[20:23], v[148:151], v[180:183], v[20:23]
	v_mfma_f32_16x16x32_bf16 v[16:19], v[156:159], v[180:183], v[16:19]
	v_mfma_f32_16x16x32_bf16 v[4:7], v[148:151], v[188:191], v[4:7]
	v_mfma_f32_16x16x32_bf16 v[0:3], v[156:159], v[188:191], v[0:3]
	s_setprio 0
	s_barrier
	s_add_i32 s81, 0, 0x18000
	s_add_i32 s85, 0, 0x1c000
	v_add_u32_e32 v140, s81, v249
	v_add_u32_e32 v156, s85, v249
	ds_read_b128 v[124:127], v140
	ds_read_b128 v[128:131], v140 offset:1024
	ds_read_b128 v[132:135], v140 offset:2048
	ds_read_b128 v[140:143], v140 offset:3072
	ds_read_b128 v[144:147], v156
	ds_read_b128 v[148:151], v156 offset:1024
	ds_read_b128 v[152:155], v156 offset:2048
	ds_read_b128 v[156:159], v156 offset:3072
	s_add_u32 s40, s40, s24
	s_addc_u32 s41, s41, 0
	s_mov_b32 m0, s16
	v_lshl_add_u64 v[220:221], s[40:41], 0, v[198:199]
	ds_read_b128 v[160:163], v251 offset:32768
	ds_read_b128 v[164:167], v251 offset:33792
	ds_read_b128 v[168:171], v251 offset:34816
	ds_read_b128 v[172:175], v251 offset:35840
	ds_read_b128 v[176:179], v251 offset:36864
	ds_read_b128 v[180:183], v251 offset:37888
	ds_read_b128 v[184:187], v251 offset:38912
	ds_read_b128 v[188:191], v251 offset:39936
	global_load_lds_dwordx4 v[220:221], off
	v_lshl_add_u64 v[220:221], s[40:41], 0, v[200:201]
	s_mov_b32 m0, s17
	s_nop 0
	global_load_lds_dwordx4 v[220:221], off
	s_waitcnt vmcnt(8) lgkmcnt(0)
	s_barrier
	s_setprio 1
	v_mfma_f32_16x16x32_bf16 v[136:139], v[124:127], v[160:163], v[136:139]
	v_mfma_f32_16x16x32_bf16 v[120:123], v[132:135], v[160:163], v[120:123]
	v_mfma_f32_16x16x32_bf16 v[108:111], v[124:127], v[168:171], v[108:111]
	v_mfma_f32_16x16x32_bf16 v[104:107], v[132:135], v[168:171], v[104:107]
	v_mfma_f32_16x16x32_bf16 v[92:95], v[124:127], v[176:179], v[92:95]
	v_mfma_f32_16x16x32_bf16 v[88:91], v[132:135], v[176:179], v[88:91]
	v_mfma_f32_16x16x32_bf16 v[76:79], v[124:127], v[184:187], v[76:79]
	v_mfma_f32_16x16x32_bf16 v[72:75], v[132:135], v[184:187], v[72:75]
	v_mfma_f32_16x16x32_bf16 v[136:139], v[128:131], v[164:167], v[136:139]
	v_mfma_f32_16x16x32_bf16 v[120:123], v[140:143], v[164:167], v[120:123]
	v_mfma_f32_16x16x32_bf16 v[108:111], v[128:131], v[172:175], v[108:111]
	v_mfma_f32_16x16x32_bf16 v[104:107], v[140:143], v[172:175], v[104:107]
	v_mfma_f32_16x16x32_bf16 v[92:95], v[128:131], v[180:183], v[92:95]
	v_mfma_f32_16x16x32_bf16 v[88:91], v[140:143], v[180:183], v[88:91]
	v_mfma_f32_16x16x32_bf16 v[76:79], v[128:131], v[188:191], v[76:79]
	v_mfma_f32_16x16x32_bf16 v[72:75], v[140:143], v[188:191], v[72:75]
	v_mfma_f32_16x16x32_bf16 v[116:119], v[144:147], v[160:163], v[116:119]
	v_mfma_f32_16x16x32_bf16 v[112:115], v[152:155], v[160:163], v[112:115]
	v_mfma_f32_16x16x32_bf16 v[100:103], v[144:147], v[168:171], v[100:103]
	v_mfma_f32_16x16x32_bf16 v[96:99], v[152:155], v[168:171], v[96:99]
	v_mfma_f32_16x16x32_bf16 v[84:87], v[144:147], v[176:179], v[84:87]
	v_mfma_f32_16x16x32_bf16 v[80:83], v[152:155], v[176:179], v[80:83]
	v_mfma_f32_16x16x32_bf16 v[68:71], v[144:147], v[184:187], v[68:71]
	v_mfma_f32_16x16x32_bf16 v[64:67], v[152:155], v[184:187], v[64:67]
	v_mfma_f32_16x16x32_bf16 v[116:119], v[148:151], v[164:167], v[116:119]
	v_mfma_f32_16x16x32_bf16 v[112:115], v[156:159], v[164:167], v[112:115]
	v_mfma_f32_16x16x32_bf16 v[100:103], v[148:151], v[172:175], v[100:103]
	v_mfma_f32_16x16x32_bf16 v[96:99], v[156:159], v[172:175], v[96:99]
	v_mfma_f32_16x16x32_bf16 v[84:87], v[148:151], v[180:183], v[84:87]
	v_mfma_f32_16x16x32_bf16 v[80:83], v[156:159], v[180:183], v[80:83]
	v_mfma_f32_16x16x32_bf16 v[68:71], v[148:151], v[188:191], v[68:71]
	v_mfma_f32_16x16x32_bf16 v[64:67], v[156:159], v[188:191], v[64:67]
	s_setprio 0
	s_barrier
; #define PG8_STAGE(bufoff, gbase, voff) do { _Pragma("unroll") for (int _i = 0; _i < 2; ++_i) \
;         __builtin_amdgcn_global_load_lds((const unsigned*)((const char*)(gbase) + (voff)[_i]), (PG8_LAS unsigned*)(lds + (bufoff) + ldsw + _i * 8192), 16, 0, 0); } while (0)
; #define PG8_LDA(dst, b, h) do { _Pragma("unroll") for (int m = 0; m < 4; ++m) _Pragma("unroll") for (int k = 0; k < 2; ++k) dst[m][k] = *(const PG8_LAS bf16x8*)(lds + PG8_SA(b, h) + aoff + m * 2048 + k * 1024); } while (0)
; #define PG8_MMA(ai, bj, At, Bt) do { __builtin_amdgcn_s_setprio(1); _Pragma("unroll") for (int m = 0; m < 4; ++m) _Pragma("unroll") for (int n = 0; n < 2; ++n) _Pragma("unroll") for (int k = 0; k < 2; ++k) \
;         acc[ai][bj][m][n] = __builtin_amdgcn_mfma_f32_16x16x32_bf16(Bt[n][k], At[m][k], acc[ai][bj][m][n], 0, 0, 0); __builtin_amdgcn_s_setprio(0); } while (0)
; #define PG8_WAIT_V(n) asm volatile("s_waitcnt vmcnt(" #n ")" ::: "memory")
; #define PG8_WAIT_L(n) asm volatile("s_waitcnt lgkmcnt(" #n ")" ::: "memory")
; #define PG8_BAR __builtin_amdgcn_s_barrier()
; #define PG8_SCHED __builtin_amdgcn_sched_barrier(0)
; template <class Epi, class Sched, bool ALIGN_EPI = false, bool SP2 = false>
; __device__ __forceinline__ void gemm_phase(PG8_LAS unsigned char* lds, const Gemm g, const Sched& S, const Epi& E) {
;     ...
;             PG8_LDA(At, 1, 1); PG8_STAGE(PG8_SB(1, 0), b3, voffB); PG8_STAGE(PG8_SB(1, 1), b3 + hstepB, voffB); PG8_STAGE(PG8_SA(1, 0), a3, voffA);
;             PG8_WAIT_V(8); PG8_WAIT_L(0); PG8_BAR; PG8_MMA(1, 0, At, B0); PG8_MMA(1, 1, At, B1); PG8_BAR; PG8_SCHED;
;     ...
;         if constexpr (ALIGN_EPI) { if (wr == 0) PG8_BAR; }
	s_add_i32 s40, s81, s11
	v_lshl_add_u64 v[208:209], v[208:209], 0, s[28:29]
	s_mov_b32 m0, s40
	ds_read_b128 v[160:163], v251 offset:49152
	ds_read_b128 v[164:167], v251 offset:50176
	ds_read_b128 v[168:171], v251 offset:51200
	ds_read_b128 v[172:175], v251 offset:52224
	ds_read_b128 v[176:179], v251 offset:53248
	ds_read_b128 v[180:183], v251 offset:54272
	ds_read_b128 v[184:187], v251 offset:55296
	ds_read_b128 v[188:191], v251 offset:56320
	global_load_lds_dwordx4 v[208:209], off
	v_lshl_add_u64 v[208:209], v[210:211], 0, s[28:29]
	s_add_i32 m0, s40, 0x2000
	s_add_i32 s40, s85, s11
	global_load_lds_dwordx4 v[208:209], off
	v_lshl_add_u64 v[208:209], v[212:213], 0, s[28:29]
	s_mov_b32 m0, s40
	s_nop 0
	global_load_lds_dwordx4 v[208:209], off
	v_lshl_add_u64 v[208:209], v[214:215], 0, s[28:29]
	s_add_i32 m0, s40, 0x2000
	s_nop 0
	global_load_lds_dwordx4 v[208:209], off
	v_lshl_add_u64 v[208:209], v[216:217], 0, s[28:29]
	s_mov_b32 m0, s26
	s_nop 0
	global_load_lds_dwordx4 v[208:209], off
	v_lshl_add_u64 v[208:209], v[218:219], 0, s[28:29]
	s_mov_b32 m0, s27
	s_nop 0
	global_load_lds_dwordx4 v[208:209], off
	s_waitcnt vmcnt(8) lgkmcnt(0)
	s_barrier
	s_setprio 1
	v_mfma_f32_16x16x32_bf16 v[60:63], v[124:127], v[160:163], v[60:63]
	v_mfma_f32_16x16x32_bf16 v[56:59], v[132:135], v[160:163], v[56:59]
	v_mfma_f32_16x16x32_bf16 v[44:47], v[124:127], v[168:171], v[44:47]
	v_mfma_f32_16x16x32_bf16 v[40:43], v[132:135], v[168:171], v[40:43]
	v_mfma_f32_16x16x32_bf16 v[28:31], v[124:127], v[176:179], v[28:31]
	v_mfma_f32_16x16x32_bf16 v[24:27], v[132:135], v[176:179], v[24:27]
	v_mfma_f32_16x16x32_bf16 v[12:15], v[124:127], v[184:187], v[12:15]
	v_mfma_f32_16x16x32_bf16 v[8:11], v[132:135], v[184:187], v[8:11]
	v_mfma_f32_16x16x32_bf16 v[60:63], v[128:131], v[164:167], v[60:63]
	v_mfma_f32_16x16x32_bf16 v[56:59], v[140:143], v[164:167], v[56:59]
	v_mfma_f32_16x16x32_bf16 v[44:47], v[128:131], v[172:175], v[44:47]
	v_mfma_f32_16x16x32_bf16 v[40:43], v[140:143], v[172:175], v[40:43]
	v_mfma_f32_16x16x32_bf16 v[28:31], v[128:131], v[180:183], v[28:31]
	v_mfma_f32_16x16x32_bf16 v[24:27], v[140:143], v[180:183], v[24:27]
	v_mfma_f32_16x16x32_bf16 v[12:15], v[128:131], v[188:191], v[12:15]
	v_mfma_f32_16x16x32_bf16 v[8:11], v[140:143], v[188:191], v[8:11]
	v_mfma_f32_16x16x32_bf16 v[52:55], v[144:147], v[160:163], v[52:55]
	v_mfma_f32_16x16x32_bf16 v[48:51], v[152:155], v[160:163], v[48:51]
	v_mfma_f32_16x16x32_bf16 v[36:39], v[144:147], v[168:171], v[36:39]
	v_mfma_f32_16x16x32_bf16 v[32:35], v[152:155], v[168:171], v[32:35]
	v_mfma_f32_16x16x32_bf16 v[20:23], v[144:147], v[176:179], v[20:23]
	v_mfma_f32_16x16x32_bf16 v[16:19], v[152:155], v[176:179], v[16:19]
	v_mfma_f32_16x16x32_bf16 v[4:7], v[144:147], v[184:187], v[4:7]
	v_mfma_f32_16x16x32_bf16 v[0:3], v[152:155], v[184:187], v[0:3]
	v_mfma_f32_16x16x32_bf16 v[52:55], v[148:151], v[164:167], v[52:55]
	v_mfma_f32_16x16x32_bf16 v[48:51], v[156:159], v[164:167], v[48:51]
	v_mfma_f32_16x16x32_bf16 v[36:39], v[148:151], v[172:175], v[36:39]
	v_mfma_f32_16x16x32_bf16 v[32:35], v[156:159], v[172:175], v[32:35]
	v_mfma_f32_16x16x32_bf16 v[20:23], v[148:151], v[180:183], v[20:23]
	v_mfma_f32_16x16x32_bf16 v[16:19], v[156:159], v[180:183], v[16:19]
	v_mfma_f32_16x16x32_bf16 v[4:7], v[148:151], v[188:191], v[4:7]
	v_mfma_f32_16x16x32_bf16 v[0:3], v[156:159], v[188:191], v[0:3]
	s_setprio 0
	s_barrier
	s_add_u32 s77, s77, 0x100
	s_addc_u32 s83, s83, 0
	s_add_u32 s78, s78, 0x100
	s_addc_u32 s79, s79, 0
	s_cmp_ge_u32 s84, s18
	s_mov_b32 s40, s84
	s_cbranch_scc0 .LBB0_380
	s_and_b64 vcc, exec, s[72:73]
	s_cbranch_vccz .LBB0_383
	s_barrier

; #define PG8_STAGE(bufoff, gbase, voff) do { _Pragma("unroll") for (int _i = 0; _i < 2; ++_i) \
;         __builtin_amdgcn_global_load_lds((const unsigned*)((const char*)(gbase) + (voff)[_i]), (PG8_LAS unsigned*)(lds + (bufoff) + ldsw + _i * 8192), 16, 0, 0); } while (0)
; #define PG8_LDA(dst, b, h) do { _Pragma("unroll") for (int m = 0; m < 4; ++m) _Pragma("unroll") for (int k = 0; k < 2; ++k) dst[m][k] = *(const PG8_LAS bf16x8*)(lds + PG8_SA(b, h) + aoff + m * 2048 + k * 1024); } while (0)
; #define PG8_LDB(dst, b, h) do { _Pragma("unroll") for (int n = 0; n < 2; ++n) _Pragma("unroll") for (int k = 0; k < 2; ++k) dst[n][k] = *(const PG8_LAS bf16x8*)(lds + PG8_SB(b, h) + boff + n * 2048 + k * 1024); } while (0)
; #define PG8_MMA(ai, bj, At, Bt) do { __builtin_amdgcn_s_setprio(1); _Pragma("unroll") for (int m = 0; m < 4; ++m) _Pragma("unroll") for (int n = 0; n < 2; ++n) _Pragma("unroll") for (int k = 0; k < 2; ++k) \
;         acc[ai][bj][m][n] = __builtin_amdgcn_mfma_f32_16x16x32_bf16(Bt[n][k], At[m][k], acc[ai][bj][m][n], 0, 0, 0); __builtin_amdgcn_s_setprio(0); } while (0)
; #define PG8_WAIT_V(n) asm volatile("s_waitcnt vmcnt(" #n ")" ::: "memory")
; #define PG8_WAIT_L(n) asm volatile("s_waitcnt lgkmcnt(" #n ")" ::: "memory")
; template <class Epi, class Sched, bool ALIGN_EPI = false, bool SP2 = false>
; __device__ __forceinline__ void gemm_phase(PG8_LAS unsigned char* lds, const Gemm g, const Sched& S, const Epi& E) {
;     ...
;             const bool last = (t == nt - 2);
;             const char* a1 = cA + (size_t)(t + 1) * kstep;
;             const char* a2 = last ? nA : cA + (size_t)(t + 2) * kstep; const char* b2 = last ? nB : cB + (size_t)(t + 2) * kstep;
;             const char* a3 = a2 + kstep; const char* b3 = b2 + kstep;
;             if (last && has_next) S.a_ready(nxt);
;             if constexpr (SP2) {
;             PG8_LDB(B0, 0, 0); PG8_LDB(B1, 0, 1); PG8_SCHED; PG8_LDA(At, 0, 0); PG8_STAGE(PG8_SA(1, 1), a1 + hstepA, voffA);
;             PG8_WAIT_V(8); PG8_WAIT_L(0); PG8_BAR; PG8_MMA(0, 0, At, B0); PG8_MMA(0, 1, At, B1); PG8_BAR; PG8_SCHED;
;             PG8_LDA(At, 0, 1); PG8_STAGE(PG8_SB(0, 0), b2, voffB); PG8_STAGE(PG8_SB(0, 1), b2 + hstepB, voffB); PG8_STAGE(PG8_SA(0, 0), a2, voffA);
;             PG8_WAIT_V(8); PG8_WAIT_L(0); PG8_BAR; PG8_MMA(1, 0, At, B0); PG8_MMA(1, 1, At, B1); PG8_BAR; PG8_SCHED;
.LBB0_426:
	s_add_i32 s89, s40, 2
	s_add_u32 s81, s44, 0x80
	s_addc_u32 s41, s45, 0
	s_add_i32 s92, 0, 0x10000
	s_cmp_eq_u32 s50, s40
	s_cselect_b32 s41, s79, s41
	s_cselect_b32 s40, s78, s81
	v_add_u32_e32 v138, s92, v143
	s_cselect_b32 s91, s85, s88
	s_cselect_b32 s90, s84, s83
	s_add_i32 s81, 0, 0x14000
	ds_read_b128 v[144:147], v138
	ds_read_b128 v[148:151], v138 offset:1024
	ds_read_b128 v[152:155], v138 offset:2048
	ds_read_b128 v[160:163], v138 offset:3072
	v_add_u32_e32 v138, s81, v143
	ds_read_b128 v[164:167], v138
	ds_read_b128 v[168:171], v138 offset:1024
	ds_read_b128 v[172:175], v138 offset:2048
	ds_read_b128 v[176:179], v138 offset:3072
	v_lshl_add_u64 v[138:139], s[44:45], 0, v[136:137]
	s_add_i32 m0, s35, 0xc000
	ds_read_b128 v[180:183], v159
	ds_read_b128 v[184:187], v159 offset:1024
	ds_read_b128 v[188:191], v159 offset:2048
	ds_read_b128 v[198:201], v159 offset:3072
	ds_read_b128 v[202:205], v159 offset:4096
	ds_read_b128 v[206:209], v159 offset:5120
	ds_read_b128 v[210:213], v159 offset:6144
	ds_read_b128 v[214:217], v159 offset:7168
	global_load_lds_dwordx4 v[138:139], off
	v_lshl_add_u64 v[138:139], s[44:45], 0, v[134:135]
	s_add_i32 m0, s35, 0xe000
	s_nop 0
	global_load_lds_dwordx4 v[138:139], off
	s_waitcnt vmcnt(8) lgkmcnt(0)
	s_barrier
	s_setprio 1
	v_mfma_f32_16x16x32_bf16 v[124:127], v[144:147], v[180:183], v[124:127]
	v_mfma_f32_16x16x32_bf16 v[120:123], v[152:155], v[180:183], v[120:123]
	v_mfma_f32_16x16x32_bf16 v[108:111], v[144:147], v[188:191], v[108:111]
	v_mfma_f32_16x16x32_bf16 v[104:107], v[152:155], v[188:191], v[104:107]
	v_mfma_f32_16x16x32_bf16 v[92:95], v[144:147], v[202:205], v[92:95]
	v_mfma_f32_16x16x32_bf16 v[88:91], v[152:155], v[202:205], v[88:91]
	v_mfma_f32_16x16x32_bf16 v[76:79], v[144:147], v[210:213], v[76:79]
	v_mfma_f32_16x16x32_bf16 v[72:75], v[152:155], v[210:213], v[72:75]
	v_mfma_f32_16x16x32_bf16 v[124:127], v[148:151], v[184:187], v[124:127]
	v_mfma_f32_16x16x32_bf16 v[120:123], v[160:163], v[184:187], v[120:123]
	v_mfma_f32_16x16x32_bf16 v[108:111], v[148:151], v[198:201], v[108:111]
	v_mfma_f32_16x16x32_bf16 v[104:107], v[160:163], v[198:201], v[104:107]
	v_mfma_f32_16x16x32_bf16 v[92:95], v[148:151], v[206:209], v[92:95]
	v_mfma_f32_16x16x32_bf16 v[88:91], v[160:163], v[206:209], v[88:91]
	v_mfma_f32_16x16x32_bf16 v[76:79], v[148:151], v[214:217], v[76:79]
	v_mfma_f32_16x16x32_bf16 v[72:75], v[160:163], v[214:217], v[72:75]
	v_mfma_f32_16x16x32_bf16 v[116:119], v[164:167], v[180:183], v[116:119]
	v_mfma_f32_16x16x32_bf16 v[112:115], v[172:175], v[180:183], v[112:115]
	v_mfma_f32_16x16x32_bf16 v[100:103], v[164:167], v[188:191], v[100:103]
	v_mfma_f32_16x16x32_bf16 v[96:99], v[172:175], v[188:191], v[96:99]
	v_mfma_f32_16x16x32_bf16 v[84:87], v[164:167], v[202:205], v[84:87]
	v_mfma_f32_16x16x32_bf16 v[80:83], v[172:175], v[202:205], v[80:83]
	v_mfma_f32_16x16x32_bf16 v[68:71], v[164:167], v[210:213], v[68:71]
	v_mfma_f32_16x16x32_bf16 v[64:67], v[172:175], v[210:213], v[64:67]
	v_mfma_f32_16x16x32_bf16 v[116:119], v[168:171], v[184:187], v[116:119]
	v_mfma_f32_16x16x32_bf16 v[112:115], v[176:179], v[184:187], v[112:115]
	v_mfma_f32_16x16x32_bf16 v[100:103], v[168:171], v[198:201], v[100:103]
	v_mfma_f32_16x16x32_bf16 v[96:99], v[176:179], v[198:201], v[96:99]
	v_mfma_f32_16x16x32_bf16 v[84:87], v[168:171], v[206:209], v[84:87]
	v_mfma_f32_16x16x32_bf16 v[80:83], v[176:179], v[206:209], v[80:83]
	v_mfma_f32_16x16x32_bf16 v[68:71], v[168:171], v[214:217], v[68:71]
	v_mfma_f32_16x16x32_bf16 v[64:67], v[176:179], v[214:217], v[64:67]
	s_setprio 0
	s_barrier
	s_add_i32 s92, s92, s17
	v_lshl_add_u64 v[138:139], s[90:91], 0, v[194:195]
	s_mov_b32 m0, s92
	ds_read_b128 v[180:183], v159 offset:16384
	ds_read_b128 v[184:187], v159 offset:17408
	ds_read_b128 v[188:191], v159 offset:18432
	ds_read_b128 v[198:201], v159 offset:19456
	ds_read_b128 v[202:205], v159 offset:20480
	ds_read_b128 v[206:209], v159 offset:21504
	ds_read_b128 v[210:213], v159 offset:22528
	ds_read_b128 v[214:217], v159 offset:23552
	global_load_lds_dwordx4 v[138:139], off
	s_add_i32 m0, s92, 0x2000
	v_lshl_add_u64 v[156:157], s[90:91], 0, v[132:133]
	s_add_u32 s90, s90, s24
	s_addc_u32 s91, s91, 0
	s_add_i32 s81, s81, s17
	global_load_lds_dwordx4 v[156:157], off
	v_lshl_add_u64 v[218:219], s[90:91], 0, v[194:195]
	s_mov_b32 m0, s81
	v_lshl_add_u64 v[220:221], s[90:91], 0, v[132:133]
	global_load_lds_dwordx4 v[218:219], off
	s_add_i32 m0, s81, 0x2000
	v_lshl_add_u64 v[222:223], s[40:41], 0, v[128:129]
	global_load_lds_dwordx4 v[220:221], off
	s_mov_b32 m0, s35
	v_lshl_add_u64 v[224:225], s[40:41], 0, v[130:131]
	global_load_lds_dwordx4 v[222:223], off
	s_mov_b32 m0, s36
	s_nop 0
	global_load_lds_dwordx4 v[224:225], off
	s_waitcnt vmcnt(8) lgkmcnt(0)
	s_barrier
; #define PG8_STAGE(bufoff, gbase, voff) do { _Pragma("unroll") for (int _i = 0; _i < 2; ++_i) \
;         __builtin_amdgcn_global_load_lds((const unsigned*)((const char*)(gbase) + (voff)[_i]), (PG8_LAS unsigned*)(lds + (bufoff) + ldsw + _i * 8192), 16, 0, 0); } while (0)
; #define PG8_LDA(dst, b, h) do { _Pragma("unroll") for (int m = 0; m < 4; ++m) _Pragma("unroll") for (int k = 0; k < 2; ++k) dst[m][k] = *(const PG8_LAS bf16x8*)(lds + PG8_SA(b, h) + aoff + m * 2048 + k * 1024); } while (0)
; #define PG8_LDB(dst, b, h) do { _Pragma("unroll") for (int n = 0; n < 2; ++n) _Pragma("unroll") for (int k = 0; k < 2; ++k) dst[n][k] = *(const PG8_LAS bf16x8*)(lds + PG8_SB(b, h) + boff + n * 2048 + k * 1024); } while (0)
; #define PG8_MMA(ai, bj, At, Bt) do { __builtin_amdgcn_s_setprio(1); _Pragma("unroll") for (int m = 0; m < 4; ++m) _Pragma("unroll") for (int n = 0; n < 2; ++n) _Pragma("unroll") for (int k = 0; k < 2; ++k) \
;         acc[ai][bj][m][n] = __builtin_amdgcn_mfma_f32_16x16x32_bf16(Bt[n][k], At[m][k], acc[ai][bj][m][n], 0, 0, 0); __builtin_amdgcn_s_setprio(0); } while (0)
; #define PG8_WAIT_V(n) asm volatile("s_waitcnt vmcnt(" #n ")" ::: "memory")
; #define PG8_WAIT_L(n) asm volatile("s_waitcnt lgkmcnt(" #n ")" ::: "memory")
; #define PG8_BAR __builtin_amdgcn_s_barrier()
; #define PG8_SCHED __builtin_amdgcn_sched_barrier(0)
; template <class Epi, class Sched, bool ALIGN_EPI = false, bool SP2 = false>
; __device__ __forceinline__ void gemm_phase(PG8_LAS unsigned char* lds, const Gemm g, const Sched& S, const Epi& E) {
;     ...
;             PG8_WAIT_V(8); PG8_WAIT_L(0); PG8_BAR; PG8_MMA(1, 0, At, B0); PG8_MMA(1, 1, At, B1); PG8_BAR; PG8_SCHED;
;             PG8_LDB(B0, 1, 0); PG8_LDB(B1, 1, 1); PG8_SCHED; PG8_LDA(At, 1, 0); PG8_STAGE(PG8_SA(0, 1), a2 + hstepA, voffA);
;             PG8_WAIT_V(8); PG8_WAIT_L(0); PG8_BAR; PG8_MMA(0, 0, At, B0); PG8_MMA(0, 1, At, B1); PG8_BAR; PG8_SCHED;
	s_setprio 1
	v_mfma_f32_16x16x32_bf16 v[60:63], v[144:147], v[180:183], v[60:63]
	v_mfma_f32_16x16x32_bf16 v[56:59], v[152:155], v[180:183], v[56:59]
	v_mfma_f32_16x16x32_bf16 v[44:47], v[144:147], v[188:191], v[44:47]
	v_mfma_f32_16x16x32_bf16 v[40:43], v[152:155], v[188:191], v[40:43]
	v_mfma_f32_16x16x32_bf16 v[28:31], v[144:147], v[202:205], v[28:31]
	v_mfma_f32_16x16x32_bf16 v[24:27], v[152:155], v[202:205], v[24:27]
	v_mfma_f32_16x16x32_bf16 v[12:15], v[144:147], v[210:213], v[12:15]
	v_mfma_f32_16x16x32_bf16 v[8:11], v[152:155], v[210:213], v[8:11]
	v_mfma_f32_16x16x32_bf16 v[60:63], v[148:151], v[184:187], v[60:63]
	v_mfma_f32_16x16x32_bf16 v[56:59], v[160:163], v[184:187], v[56:59]
	v_mfma_f32_16x16x32_bf16 v[44:47], v[148:151], v[198:201], v[44:47]
	v_mfma_f32_16x16x32_bf16 v[40:43], v[160:163], v[198:201], v[40:43]
	v_mfma_f32_16x16x32_bf16 v[28:31], v[148:151], v[206:209], v[28:31]
	v_mfma_f32_16x16x32_bf16 v[24:27], v[160:163], v[206:209], v[24:27]
	v_mfma_f32_16x16x32_bf16 v[12:15], v[148:151], v[214:217], v[12:15]
	v_mfma_f32_16x16x32_bf16 v[8:11], v[160:163], v[214:217], v[8:11]
	v_mfma_f32_16x16x32_bf16 v[52:55], v[164:167], v[180:183], v[52:55]
	v_mfma_f32_16x16x32_bf16 v[48:51], v[172:175], v[180:183], v[48:51]
	v_mfma_f32_16x16x32_bf16 v[36:39], v[164:167], v[188:191], v[36:39]
	v_mfma_f32_16x16x32_bf16 v[32:35], v[172:175], v[188:191], v[32:35]
	v_mfma_f32_16x16x32_bf16 v[20:23], v[164:167], v[202:205], v[20:23]
	v_mfma_f32_16x16x32_bf16 v[16:19], v[172:175], v[202:205], v[16:19]
	v_mfma_f32_16x16x32_bf16 v[4:7], v[164:167], v[210:213], v[4:7]
	v_mfma_f32_16x16x32_bf16 v[0:3], v[172:175], v[210:213], v[0:3]
	v_mfma_f32_16x16x32_bf16 v[52:55], v[168:171], v[184:187], v[52:55]
	v_mfma_f32_16x16x32_bf16 v[48:51], v[176:179], v[184:187], v[48:51]
	v_mfma_f32_16x16x32_bf16 v[36:39], v[168:171], v[198:201], v[36:39]
	v_mfma_f32_16x16x32_bf16 v[32:35], v[176:179], v[198:201], v[32:35]
	v_mfma_f32_16x16x32_bf16 v[20:23], v[168:171], v[206:209], v[20:23]
	v_mfma_f32_16x16x32_bf16 v[16:19], v[176:179], v[206:209], v[16:19]
	v_mfma_f32_16x16x32_bf16 v[4:7], v[168:171], v[214:217], v[4:7]
	v_mfma_f32_16x16x32_bf16 v[0:3], v[176:179], v[214:217], v[0:3]
	s_setprio 0
	s_barrier
	s_add_i32 s81, 0, 0x18000
	v_add_u32_e32 v140, s81, v143
	s_add_i32 s90, 0, 0x1c000
	ds_read_b128 v[144:147], v140
	ds_read_b128 v[148:151], v140 offset:1024
	ds_read_b128 v[152:155], v140 offset:2048
	ds_read_b128 v[160:163], v140 offset:3072
	v_add_u32_e32 v140, s90, v143
	ds_read_b128 v[164:167], v140
	ds_read_b128 v[168:171], v140 offset:1024
	ds_read_b128 v[172:175], v140 offset:2048
	ds_read_b128 v[176:179], v140 offset:3072
	s_add_u32 s40, s40, s24
	s_addc_u32 s41, s41, 0
	s_mov_b32 m0, s37
	v_lshl_add_u64 v[242:243], s[40:41], 0, v[128:129]
	ds_read_b128 v[180:183], v159 offset:32768
	ds_read_b128 v[184:187], v159 offset:33792
	ds_read_b128 v[188:191], v159 offset:34816
	ds_read_b128 v[198:201], v159 offset:35840
	ds_read_b128 v[202:205], v159 offset:36864
	ds_read_b128 v[206:209], v159 offset:37888
	ds_read_b128 v[210:213], v159 offset:38912
	ds_read_b128 v[214:217], v159 offset:39936
	global_load_lds_dwordx4 v[242:243], off
	v_lshl_add_u64 v[242:243], s[40:41], 0, v[130:131]
	s_mov_b32 m0, s46
	s_nop 0
	global_load_lds_dwordx4 v[242:243], off
	s_waitcnt vmcnt(8) lgkmcnt(0)
	s_barrier
	s_setprio 1
	v_mfma_f32_16x16x32_bf16 v[124:127], v[144:147], v[180:183], v[124:127]
	v_mfma_f32_16x16x32_bf16 v[120:123], v[152:155], v[180:183], v[120:123]
	v_mfma_f32_16x16x32_bf16 v[108:111], v[144:147], v[188:191], v[108:111]
	v_mfma_f32_16x16x32_bf16 v[104:107], v[152:155], v[188:191], v[104:107]
	v_mfma_f32_16x16x32_bf16 v[92:95], v[144:147], v[202:205], v[92:95]
	v_mfma_f32_16x16x32_bf16 v[88:91], v[152:155], v[202:205], v[88:91]
	v_mfma_f32_16x16x32_bf16 v[76:79], v[144:147], v[210:213], v[76:79]
	v_mfma_f32_16x16x32_bf16 v[72:75], v[152:155], v[210:213], v[72:75]
	v_mfma_f32_16x16x32_bf16 v[124:127], v[148:151], v[184:187], v[124:127]
	v_mfma_f32_16x16x32_bf16 v[120:123], v[160:163], v[184:187], v[120:123]
	v_mfma_f32_16x16x32_bf16 v[108:111], v[148:151], v[198:201], v[108:111]
	v_mfma_f32_16x16x32_bf16 v[104:107], v[160:163], v[198:201], v[104:107]
	v_mfma_f32_16x16x32_bf16 v[92:95], v[148:151], v[206:209], v[92:95]
	v_mfma_f32_16x16x32_bf16 v[88:91], v[160:163], v[206:209], v[88:91]
	v_mfma_f32_16x16x32_bf16 v[76:79], v[148:151], v[214:217], v[76:79]
	v_mfma_f32_16x16x32_bf16 v[72:75], v[160:163], v[214:217], v[72:75]
	v_mfma_f32_16x16x32_bf16 v[116:119], v[164:167], v[180:183], v[116:119]
	v_mfma_f32_16x16x32_bf16 v[112:115], v[172:175], v[180:183], v[112:115]
	v_mfma_f32_16x16x32_bf16 v[100:103], v[164:167], v[188:191], v[100:103]
	v_mfma_f32_16x16x32_bf16 v[96:99], v[172:175], v[188:191], v[96:99]
	v_mfma_f32_16x16x32_bf16 v[84:87], v[164:167], v[202:205], v[84:87]
	v_mfma_f32_16x16x32_bf16 v[80:83], v[172:175], v[202:205], v[80:83]
	v_mfma_f32_16x16x32_bf16 v[68:71], v[164:167], v[210:213], v[68:71]
	v_mfma_f32_16x16x32_bf16 v[64:67], v[172:175], v[210:213], v[64:67]
	v_mfma_f32_16x16x32_bf16 v[116:119], v[168:171], v[184:187], v[116:119]
	v_mfma_f32_16x16x32_bf16 v[112:115], v[176:179], v[184:187], v[112:115]
	v_mfma_f32_16x16x32_bf16 v[100:103], v[168:171], v[198:201], v[100:103]
	v_mfma_f32_16x16x32_bf16 v[96:99], v[176:179], v[198:201], v[96:99]
	v_mfma_f32_16x16x32_bf16 v[84:87], v[168:171], v[206:209], v[84:87]
	v_mfma_f32_16x16x32_bf16 v[80:83], v[176:179], v[206:209], v[80:83]
	v_mfma_f32_16x16x32_bf16 v[68:71], v[168:171], v[214:217], v[68:71]
	v_mfma_f32_16x16x32_bf16 v[64:67], v[176:179], v[214:217], v[64:67]
	s_setprio 0
	s_barrier
; #define PG8_STAGE(bufoff, gbase, voff) do { _Pragma("unroll") for (int _i = 0; _i < 2; ++_i) \
;         __builtin_amdgcn_global_load_lds((const unsigned*)((const char*)(gbase) + (voff)[_i]), (PG8_LAS unsigned*)(lds + (bufoff) + ldsw + _i * 8192), 16, 0, 0); } while (0)
; #define PG8_LDA(dst, b, h) do { _Pragma("unroll") for (int m = 0; m < 4; ++m) _Pragma("unroll") for (int k = 0; k < 2; ++k) dst[m][k] = *(const PG8_LAS bf16x8*)(lds + PG8_SA(b, h) + aoff + m * 2048 + k * 1024); } while (0)
; #define PG8_MMA(ai, bj, At, Bt) do { __builtin_amdgcn_s_setprio(1); _Pragma("unroll") for (int m = 0; m < 4; ++m) _Pragma("unroll") for (int n = 0; n < 2; ++n) _Pragma("unroll") for (int k = 0; k < 2; ++k) \
;         acc[ai][bj][m][n] = __builtin_amdgcn_mfma_f32_16x16x32_bf16(Bt[n][k], At[m][k], acc[ai][bj][m][n], 0, 0, 0); __builtin_amdgcn_s_setprio(0); } while (0)
; #define PG8_WAIT_V(n) asm volatile("s_waitcnt vmcnt(" #n ")" ::: "memory")
; #define PG8_WAIT_L(n) asm volatile("s_waitcnt lgkmcnt(" #n ")" ::: "memory")
; #define PG8_BAR __builtin_amdgcn_s_barrier()
; #define PG8_SCHED __builtin_amdgcn_sched_barrier(0)
; template <class Epi, class Sched, bool ALIGN_EPI = false, bool SP2 = false>
; __device__ __forceinline__ void gemm_phase(PG8_LAS unsigned char* lds, const Gemm g, const Sched& S, const Epi& E) {
;     ...
;             PG8_LDA(At, 1, 1); PG8_STAGE(PG8_SB(1, 0), b3, voffB); PG8_STAGE(PG8_SB(1, 1), b3 + hstepB, voffB); PG8_STAGE(PG8_SA(1, 0), a3, voffA);
;             PG8_WAIT_V(8); PG8_WAIT_L(0); PG8_BAR; PG8_MMA(1, 0, At, B0); PG8_MMA(1, 1, At, B1); PG8_BAR; PG8_SCHED;
;     ...
;         if constexpr (ALIGN_EPI) { if (wr == 0) PG8_BAR; }
	s_add_i32 s40, s81, s17
	v_lshl_add_u64 v[138:139], v[138:139], 0, s[28:29]
	s_mov_b32 m0, s40
	ds_read_b128 v[180:183], v159 offset:49152
	ds_read_b128 v[184:187], v159 offset:50176
	ds_read_b128 v[188:191], v159 offset:51200
	ds_read_b128 v[198:201], v159 offset:52224
	ds_read_b128 v[202:205], v159 offset:53248
	ds_read_b128 v[206:209], v159 offset:54272
	ds_read_b128 v[210:213], v159 offset:55296
	ds_read_b128 v[214:217], v159 offset:56320
	global_load_lds_dwordx4 v[138:139], off
	v_lshl_add_u64 v[138:139], v[156:157], 0, s[28:29]
	s_add_i32 m0, s40, 0x2000
	s_add_i32 s40, s90, s17
	global_load_lds_dwordx4 v[138:139], off
	v_lshl_add_u64 v[138:139], v[218:219], 0, s[28:29]
	s_mov_b32 m0, s40
	s_nop 0
	global_load_lds_dwordx4 v[138:139], off
	v_lshl_add_u64 v[138:139], v[220:221], 0, s[28:29]
	s_add_i32 m0, s40, 0x2000
	s_nop 0
	global_load_lds_dwordx4 v[138:139], off
	v_lshl_add_u64 v[138:139], v[222:223], 0, s[28:29]
	s_mov_b32 m0, s48
	s_nop 0
	global_load_lds_dwordx4 v[138:139], off
	v_lshl_add_u64 v[138:139], v[224:225], 0, s[28:29]
	s_mov_b32 m0, s49
	s_nop 0
	global_load_lds_dwordx4 v[138:139], off
	s_waitcnt vmcnt(8) lgkmcnt(0)
	s_barrier
	s_setprio 1
	v_mfma_f32_16x16x32_bf16 v[60:63], v[144:147], v[180:183], v[60:63]
	v_mfma_f32_16x16x32_bf16 v[56:59], v[152:155], v[180:183], v[56:59]
	v_mfma_f32_16x16x32_bf16 v[44:47], v[144:147], v[188:191], v[44:47]
	v_mfma_f32_16x16x32_bf16 v[40:43], v[152:155], v[188:191], v[40:43]
	v_mfma_f32_16x16x32_bf16 v[28:31], v[144:147], v[202:205], v[28:31]
	v_mfma_f32_16x16x32_bf16 v[24:27], v[152:155], v[202:205], v[24:27]
	v_mfma_f32_16x16x32_bf16 v[12:15], v[144:147], v[210:213], v[12:15]
	v_mfma_f32_16x16x32_bf16 v[8:11], v[152:155], v[210:213], v[8:11]
	v_mfma_f32_16x16x32_bf16 v[60:63], v[148:151], v[184:187], v[60:63]
	v_mfma_f32_16x16x32_bf16 v[56:59], v[160:163], v[184:187], v[56:59]
	v_mfma_f32_16x16x32_bf16 v[44:47], v[148:151], v[198:201], v[44:47]
	v_mfma_f32_16x16x32_bf16 v[40:43], v[160:163], v[198:201], v[40:43]
	v_mfma_f32_16x16x32_bf16 v[28:31], v[148:151], v[206:209], v[28:31]
	v_mfma_f32_16x16x32_bf16 v[24:27], v[160:163], v[206:209], v[24:27]
	v_mfma_f32_16x16x32_bf16 v[12:15], v[148:151], v[214:217], v[12:15]
	v_mfma_f32_16x16x32_bf16 v[8:11], v[160:163], v[214:217], v[8:11]
	v_mfma_f32_16x16x32_bf16 v[52:55], v[164:167], v[180:183], v[52:55]
	v_mfma_f32_16x16x32_bf16 v[48:51], v[172:175], v[180:183], v[48:51]
	v_mfma_f32_16x16x32_bf16 v[36:39], v[164:167], v[188:191], v[36:39]
	v_mfma_f32_16x16x32_bf16 v[32:35], v[172:175], v[188:191], v[32:35]
	v_mfma_f32_16x16x32_bf16 v[20:23], v[164:167], v[202:205], v[20:23]
	v_mfma_f32_16x16x32_bf16 v[16:19], v[172:175], v[202:205], v[16:19]
	v_mfma_f32_16x16x32_bf16 v[4:7], v[164:167], v[210:213], v[4:7]
	v_mfma_f32_16x16x32_bf16 v[0:3], v[172:175], v[210:213], v[0:3]
	v_mfma_f32_16x16x32_bf16 v[52:55], v[168:171], v[184:187], v[52:55]
	v_mfma_f32_16x16x32_bf16 v[48:51], v[176:179], v[184:187], v[48:51]
	v_mfma_f32_16x16x32_bf16 v[36:39], v[168:171], v[198:201], v[36:39]
	v_mfma_f32_16x16x32_bf16 v[32:35], v[176:179], v[198:201], v[32:35]
	v_mfma_f32_16x16x32_bf16 v[20:23], v[168:171], v[206:209], v[20:23]
	v_mfma_f32_16x16x32_bf16 v[16:19], v[176:179], v[206:209], v[16:19]
	v_mfma_f32_16x16x32_bf16 v[4:7], v[168:171], v[214:217], v[4:7]
	v_mfma_f32_16x16x32_bf16 v[0:3], v[176:179], v[214:217], v[0:3]
	s_setprio 0
	s_barrier
	s_add_u32 s83, s83, 0x100
	s_addc_u32 s88, s88, 0
	s_add_u32 s44, s44, 0x100
	s_addc_u32 s45, s45, 0
	s_cmp_ge_u32 s89, s47
	s_mov_b32 s40, s89
	s_cbranch_scc0 .LBB0_426
	s_and_b64 vcc, exec, s[72:73]
	s_cbranch_vccz .LBB0_429
	s_barrier

; #define PG8_STAGE(bufoff, gbase, voff) do { _Pragma("unroll") for (int _i = 0; _i < 2; ++_i) \
;         __builtin_amdgcn_global_load_lds((const unsigned*)((const char*)(gbase) + (voff)[_i]), (PG8_LAS unsigned*)(lds + (bufoff) + ldsw + _i * 8192), 16, 0, 0); } while (0)
; #define PG8_LDA(dst, b, h) do { _Pragma("unroll") for (int m = 0; m < 4; ++m) _Pragma("unroll") for (int k = 0; k < 2; ++k) dst[m][k] = *(const PG8_LAS bf16x8*)(lds + PG8_SA(b, h) + aoff + m * 2048 + k * 1024); } while (0)
; #define PG8_LDB(dst, b, h) do { _Pragma("unroll") for (int n = 0; n < 2; ++n) _Pragma("unroll") for (int k = 0; k < 2; ++k) dst[n][k] = *(const PG8_LAS bf16x8*)(lds + PG8_SB(b, h) + boff + n * 2048 + k * 1024); } while (0)
; #define PG8_MMA(ai, bj, At, Bt) do { __builtin_amdgcn_s_setprio(1); _Pragma("unroll") for (int m = 0; m < 4; ++m) _Pragma("unroll") for (int n = 0; n < 2; ++n) _Pragma("unroll") for (int k = 0; k < 2; ++k) \
;         acc[ai][bj][m][n] = __builtin_amdgcn_mfma_f32_16x16x32_bf16(Bt[n][k], At[m][k], acc[ai][bj][m][n], 0, 0, 0); __builtin_amdgcn_s_setprio(0); } while (0)
; #define PG8_WAIT_V(n) asm volatile("s_waitcnt vmcnt(" #n ")" ::: "memory")
; #define PG8_WAIT_L(n) asm volatile("s_waitcnt lgkmcnt(" #n ")" ::: "memory")
; template <class Epi, class Sched, bool ALIGN_EPI = false, bool SP2 = false>
; __device__ __forceinline__ void gemm_phase(PG8_LAS unsigned char* lds, const Gemm g, const Sched& S, const Epi& E) {
;     ...
;             const bool last = (t == nt - 2);
;             const char* a1 = cA + (size_t)(t + 1) * kstep;
;             const char* a2 = last ? nA : cA + (size_t)(t + 2) * kstep; const char* b2 = last ? nB : cB + (size_t)(t + 2) * kstep;
;             const char* a3 = a2 + kstep; const char* b3 = b2 + kstep;
;             if (last && has_next) S.a_ready(nxt);
;             if constexpr (SP2) {
;             PG8_LDB(B0, 0, 0); PG8_LDB(B1, 0, 1); PG8_SCHED; PG8_LDA(At, 0, 0); PG8_STAGE(PG8_SA(1, 1), a1 + hstepA, voffA);
;             PG8_WAIT_V(8); PG8_WAIT_L(0); PG8_BAR; PG8_MMA(0, 0, At, B0); PG8_MMA(0, 1, At, B1); PG8_BAR; PG8_SCHED;
;             PG8_LDA(At, 0, 1); PG8_STAGE(PG8_SB(0, 0), b2, voffB); PG8_STAGE(PG8_SB(0, 1), b2 + hstepB, voffB); PG8_STAGE(PG8_SA(0, 0), a2, voffA);
;             PG8_WAIT_V(8); PG8_WAIT_L(0); PG8_BAR; PG8_MMA(1, 0, At, B0); PG8_MMA(1, 1, At, B1); PG8_BAR; PG8_SCHED;
.LBB0_460:
	s_add_i32 s76, s40, 2
	s_add_u32 s77, s44, 0x80
	s_addc_u32 s41, s45, 0
	s_add_i32 s81, 0, 0x10000
	s_cmp_eq_u32 s13, s40
	s_cselect_b32 s41, s87, s41
	s_cselect_b32 s40, s86, s77
	s_cselect_b32 s91, s79, vcc_hi
	s_cselect_b32 s90, s78, vcc_lo
	s_add_i32 s77, 0, 0x14000
	v_add_u32_e32 v154, s81, v165
	v_add_u32_e32 v162, s77, v165
	ds_read_b128 v[142:145], v154
	ds_read_b128 v[146:149], v154 offset:1024
	ds_read_b128 v[150:153], v154 offset:2048
	ds_read_b128 v[154:157], v154 offset:3072
	ds_read_b128 v[158:161], v162
	ds_read_b128 v[168:171], v162 offset:1024
	ds_read_b128 v[172:175], v162 offset:2048
	ds_read_b128 v[176:179], v162 offset:3072
	v_lshl_add_u64 v[162:163], s[44:45], 0, v[140:141]
	s_add_i32 m0, s57, 0xc000
	ds_read_b128 v[180:183], v167
	ds_read_b128 v[184:187], v167 offset:1024
	ds_read_b128 v[188:191], v167 offset:2048
	ds_read_b128 v[198:201], v167 offset:3072
	ds_read_b128 v[202:205], v167 offset:4096
	ds_read_b128 v[206:209], v167 offset:5120
	ds_read_b128 v[210:213], v167 offset:6144
	ds_read_b128 v[214:217], v167 offset:7168
	global_load_lds_dwordx4 v[162:163], off
	v_lshl_add_u64 v[162:163], s[44:45], 0, v[138:139]
	s_add_i32 m0, s57, 0xe000
	s_nop 0
	global_load_lds_dwordx4 v[162:163], off
	s_waitcnt vmcnt(8) lgkmcnt(0)
	s_barrier
	s_setprio 1
	v_mfma_f32_16x16x32_bf16 v[124:127], v[142:145], v[180:183], v[124:127]
	v_mfma_f32_16x16x32_bf16 v[120:123], v[150:153], v[180:183], v[120:123]
	v_mfma_f32_16x16x32_bf16 v[108:111], v[142:145], v[188:191], v[108:111]
	v_mfma_f32_16x16x32_bf16 v[104:107], v[150:153], v[188:191], v[104:107]
	v_mfma_f32_16x16x32_bf16 v[92:95], v[142:145], v[202:205], v[92:95]
	v_mfma_f32_16x16x32_bf16 v[88:91], v[150:153], v[202:205], v[88:91]
	v_mfma_f32_16x16x32_bf16 v[76:79], v[142:145], v[210:213], v[76:79]
	v_mfma_f32_16x16x32_bf16 v[72:75], v[150:153], v[210:213], v[72:75]
	v_mfma_f32_16x16x32_bf16 v[124:127], v[146:149], v[184:187], v[124:127]
	v_mfma_f32_16x16x32_bf16 v[120:123], v[154:157], v[184:187], v[120:123]
	v_mfma_f32_16x16x32_bf16 v[108:111], v[146:149], v[198:201], v[108:111]
	v_mfma_f32_16x16x32_bf16 v[104:107], v[154:157], v[198:201], v[104:107]
	v_mfma_f32_16x16x32_bf16 v[92:95], v[146:149], v[206:209], v[92:95]
	v_mfma_f32_16x16x32_bf16 v[88:91], v[154:157], v[206:209], v[88:91]
	v_mfma_f32_16x16x32_bf16 v[76:79], v[146:149], v[214:217], v[76:79]
	v_mfma_f32_16x16x32_bf16 v[72:75], v[154:157], v[214:217], v[72:75]
	v_mfma_f32_16x16x32_bf16 v[116:119], v[158:161], v[180:183], v[116:119]
	v_mfma_f32_16x16x32_bf16 v[112:115], v[172:175], v[180:183], v[112:115]
	v_mfma_f32_16x16x32_bf16 v[100:103], v[158:161], v[188:191], v[100:103]
	v_mfma_f32_16x16x32_bf16 v[96:99], v[172:175], v[188:191], v[96:99]
	v_mfma_f32_16x16x32_bf16 v[84:87], v[158:161], v[202:205], v[84:87]
	v_mfma_f32_16x16x32_bf16 v[80:83], v[172:175], v[202:205], v[80:83]
	v_mfma_f32_16x16x32_bf16 v[68:71], v[158:161], v[210:213], v[68:71]
	v_mfma_f32_16x16x32_bf16 v[64:67], v[172:175], v[210:213], v[64:67]
	v_mfma_f32_16x16x32_bf16 v[116:119], v[168:171], v[184:187], v[116:119]
	v_mfma_f32_16x16x32_bf16 v[112:115], v[176:179], v[184:187], v[112:115]
	v_mfma_f32_16x16x32_bf16 v[100:103], v[168:171], v[198:201], v[100:103]
	v_mfma_f32_16x16x32_bf16 v[96:99], v[176:179], v[198:201], v[96:99]
	v_mfma_f32_16x16x32_bf16 v[84:87], v[168:171], v[206:209], v[84:87]
	v_mfma_f32_16x16x32_bf16 v[80:83], v[176:179], v[206:209], v[80:83]
	v_mfma_f32_16x16x32_bf16 v[68:71], v[168:171], v[214:217], v[68:71]
	v_mfma_f32_16x16x32_bf16 v[64:67], v[176:179], v[214:217], v[64:67]
	s_setprio 0
	s_barrier
	s_add_i32 s81, s81, s56
	v_lshl_add_u64 v[162:163], s[90:91], 0, v[130:131]
	s_mov_b32 m0, s81
	ds_read_b128 v[180:183], v167 offset:16384
	ds_read_b128 v[184:187], v167 offset:17408
	ds_read_b128 v[188:191], v167 offset:18432
	ds_read_b128 v[198:201], v167 offset:19456
	ds_read_b128 v[202:205], v167 offset:20480
	ds_read_b128 v[206:209], v167 offset:21504
	ds_read_b128 v[210:213], v167 offset:22528
	ds_read_b128 v[214:217], v167 offset:23552
	global_load_lds_dwordx4 v[162:163], off
	s_add_i32 m0, s81, 0x2000
	v_lshl_add_u64 v[218:219], s[90:91], 0, v[134:135]
	s_add_u32 s90, s90, s24
	s_addc_u32 s91, s91, 0
	s_add_i32 s77, s77, s56
	global_load_lds_dwordx4 v[218:219], off
	v_lshl_add_u64 v[220:221], s[90:91], 0, v[130:131]
	s_mov_b32 m0, s77
	v_lshl_add_u64 v[222:223], s[90:91], 0, v[134:135]
	global_load_lds_dwordx4 v[220:221], off
	s_add_i32 m0, s77, 0x2000
	v_lshl_add_u64 v[224:225], s[40:41], 0, v[128:129]
	global_load_lds_dwordx4 v[222:223], off
	s_mov_b32 m0, s57
	v_lshl_add_u64 v[250:251], s[40:41], 0, v[132:133]
	global_load_lds_dwordx4 v[224:225], off
	s_mov_b32 m0, s48
	s_nop 0
	global_load_lds_dwordx4 v[250:251], off
	s_waitcnt vmcnt(8) lgkmcnt(0)
	s_barrier
; #define PG8_STAGE(bufoff, gbase, voff) do { _Pragma("unroll") for (int _i = 0; _i < 2; ++_i) \
;         __builtin_amdgcn_global_load_lds((const unsigned*)((const char*)(gbase) + (voff)[_i]), (PG8_LAS unsigned*)(lds + (bufoff) + ldsw + _i * 8192), 16, 0, 0); } while (0)
; #define PG8_LDA(dst, b, h) do { _Pragma("unroll") for (int m = 0; m < 4; ++m) _Pragma("unroll") for (int k = 0; k < 2; ++k) dst[m][k] = *(const PG8_LAS bf16x8*)(lds + PG8_SA(b, h) + aoff + m * 2048 + k * 1024); } while (0)
; #define PG8_LDB(dst, b, h) do { _Pragma("unroll") for (int n = 0; n < 2; ++n) _Pragma("unroll") for (int k = 0; k < 2; ++k) dst[n][k] = *(const PG8_LAS bf16x8*)(lds + PG8_SB(b, h) + boff + n * 2048 + k * 1024); } while (0)
; #define PG8_MMA(ai, bj, At, Bt) do { __builtin_amdgcn_s_setprio(1); _Pragma("unroll") for (int m = 0; m < 4; ++m) _Pragma("unroll") for (int n = 0; n < 2; ++n) _Pragma("unroll") for (int k = 0; k < 2; ++k) \
;         acc[ai][bj][m][n] = __builtin_amdgcn_mfma_f32_16x16x32_bf16(Bt[n][k], At[m][k], acc[ai][bj][m][n], 0, 0, 0); __builtin_amdgcn_s_setprio(0); } while (0)
; #define PG8_WAIT_V(n) asm volatile("s_waitcnt vmcnt(" #n ")" ::: "memory")
; #define PG8_WAIT_L(n) asm volatile("s_waitcnt lgkmcnt(" #n ")" ::: "memory")
; #define PG8_BAR __builtin_amdgcn_s_barrier()
; #define PG8_SCHED __builtin_amdgcn_sched_barrier(0)
; template <class Epi, class Sched, bool ALIGN_EPI = false, bool SP2 = false>
; __device__ __forceinline__ void gemm_phase(PG8_LAS unsigned char* lds, const Gemm g, const Sched& S, const Epi& E) {
;     ...
;             PG8_WAIT_V(8); PG8_WAIT_L(0); PG8_BAR; PG8_MMA(1, 0, At, B0); PG8_MMA(1, 1, At, B1); PG8_BAR; PG8_SCHED;
;             PG8_LDB(B0, 1, 0); PG8_LDB(B1, 1, 1); PG8_SCHED; PG8_LDA(At, 1, 0); PG8_STAGE(PG8_SA(0, 1), a2 + hstepA, voffA);
;             PG8_WAIT_V(8); PG8_WAIT_L(0); PG8_BAR; PG8_MMA(0, 0, At, B0); PG8_MMA(0, 1, At, B1); PG8_BAR; PG8_SCHED;
	s_setprio 1
	v_mfma_f32_16x16x32_bf16 v[60:63], v[142:145], v[180:183], v[60:63]
	v_mfma_f32_16x16x32_bf16 v[56:59], v[150:153], v[180:183], v[56:59]
	v_mfma_f32_16x16x32_bf16 v[44:47], v[142:145], v[188:191], v[44:47]
	v_mfma_f32_16x16x32_bf16 v[40:43], v[150:153], v[188:191], v[40:43]
	v_mfma_f32_16x16x32_bf16 v[28:31], v[142:145], v[202:205], v[28:31]
	v_mfma_f32_16x16x32_bf16 v[24:27], v[150:153], v[202:205], v[24:27]
	v_mfma_f32_16x16x32_bf16 v[12:15], v[142:145], v[210:213], v[12:15]
	v_mfma_f32_16x16x32_bf16 v[8:11], v[150:153], v[210:213], v[8:11]
	v_mfma_f32_16x16x32_bf16 v[60:63], v[146:149], v[184:187], v[60:63]
	v_mfma_f32_16x16x32_bf16 v[56:59], v[154:157], v[184:187], v[56:59]
	v_mfma_f32_16x16x32_bf16 v[44:47], v[146:149], v[198:201], v[44:47]
	v_mfma_f32_16x16x32_bf16 v[40:43], v[154:157], v[198:201], v[40:43]
	v_mfma_f32_16x16x32_bf16 v[28:31], v[146:149], v[206:209], v[28:31]
	v_mfma_f32_16x16x32_bf16 v[24:27], v[154:157], v[206:209], v[24:27]
	v_mfma_f32_16x16x32_bf16 v[12:15], v[146:149], v[214:217], v[12:15]
	v_mfma_f32_16x16x32_bf16 v[8:11], v[154:157], v[214:217], v[8:11]
	v_mfma_f32_16x16x32_bf16 v[52:55], v[158:161], v[180:183], v[52:55]
	v_mfma_f32_16x16x32_bf16 v[48:51], v[172:175], v[180:183], v[48:51]
	v_mfma_f32_16x16x32_bf16 v[36:39], v[158:161], v[188:191], v[36:39]
	v_mfma_f32_16x16x32_bf16 v[32:35], v[172:175], v[188:191], v[32:35]
	v_mfma_f32_16x16x32_bf16 v[20:23], v[158:161], v[202:205], v[20:23]
	v_mfma_f32_16x16x32_bf16 v[16:19], v[172:175], v[202:205], v[16:19]
	v_mfma_f32_16x16x32_bf16 v[4:7], v[158:161], v[210:213], v[4:7]
	v_mfma_f32_16x16x32_bf16 v[0:3], v[172:175], v[210:213], v[0:3]
	v_mfma_f32_16x16x32_bf16 v[52:55], v[168:171], v[184:187], v[52:55]
	v_mfma_f32_16x16x32_bf16 v[48:51], v[176:179], v[184:187], v[48:51]
	v_mfma_f32_16x16x32_bf16 v[36:39], v[168:171], v[198:201], v[36:39]
	v_mfma_f32_16x16x32_bf16 v[32:35], v[176:179], v[198:201], v[32:35]
	v_mfma_f32_16x16x32_bf16 v[20:23], v[168:171], v[206:209], v[20:23]
	v_mfma_f32_16x16x32_bf16 v[16:19], v[176:179], v[206:209], v[16:19]
	v_mfma_f32_16x16x32_bf16 v[4:7], v[168:171], v[214:217], v[4:7]
	v_mfma_f32_16x16x32_bf16 v[0:3], v[176:179], v[214:217], v[0:3]
	s_setprio 0
	s_barrier
	s_add_i32 s77, 0, 0x18000
	s_add_i32 s81, 0, 0x1c000
	v_add_u32_e32 v154, s77, v165
	v_add_u32_e32 v176, s81, v165
	ds_read_b128 v[142:145], v154
	ds_read_b128 v[146:149], v154 offset:1024
	ds_read_b128 v[150:153], v154 offset:2048
	ds_read_b128 v[154:157], v154 offset:3072
	ds_read_b128 v[158:161], v176
	ds_read_b128 v[168:171], v176 offset:1024
	ds_read_b128 v[172:175], v176 offset:2048
	ds_read_b128 v[176:179], v176 offset:3072
	s_add_u32 s40, s40, s24
	s_addc_u32 s41, s41, 0
	s_mov_b32 m0, s49
	v_lshl_add_u64 v[242:243], s[40:41], 0, v[128:129]
	ds_read_b128 v[180:183], v167 offset:32768
	ds_read_b128 v[184:187], v167 offset:33792
	ds_read_b128 v[188:191], v167 offset:34816
	ds_read_b128 v[198:201], v167 offset:35840
	ds_read_b128 v[202:205], v167 offset:36864
	ds_read_b128 v[206:209], v167 offset:37888
	ds_read_b128 v[210:213], v167 offset:38912
	ds_read_b128 v[214:217], v167 offset:39936
	global_load_lds_dwordx4 v[242:243], off
	v_lshl_add_u64 v[242:243], s[40:41], 0, v[132:133]
	s_mov_b32 m0, s83
	s_nop 0
	global_load_lds_dwordx4 v[242:243], off
	s_waitcnt vmcnt(8) lgkmcnt(0)
	s_barrier
	s_setprio 1
	v_mfma_f32_16x16x32_bf16 v[124:127], v[142:145], v[180:183], v[124:127]
	v_mfma_f32_16x16x32_bf16 v[120:123], v[150:153], v[180:183], v[120:123]
	v_mfma_f32_16x16x32_bf16 v[108:111], v[142:145], v[188:191], v[108:111]
	v_mfma_f32_16x16x32_bf16 v[104:107], v[150:153], v[188:191], v[104:107]
	v_mfma_f32_16x16x32_bf16 v[92:95], v[142:145], v[202:205], v[92:95]
	v_mfma_f32_16x16x32_bf16 v[88:91], v[150:153], v[202:205], v[88:91]
	v_mfma_f32_16x16x32_bf16 v[76:79], v[142:145], v[210:213], v[76:79]
	v_mfma_f32_16x16x32_bf16 v[72:75], v[150:153], v[210:213], v[72:75]
	v_mfma_f32_16x16x32_bf16 v[124:127], v[146:149], v[184:187], v[124:127]
	v_mfma_f32_16x16x32_bf16 v[120:123], v[154:157], v[184:187], v[120:123]
	v_mfma_f32_16x16x32_bf16 v[108:111], v[146:149], v[198:201], v[108:111]
	v_mfma_f32_16x16x32_bf16 v[104:107], v[154:157], v[198:201], v[104:107]
	v_mfma_f32_16x16x32_bf16 v[92:95], v[146:149], v[206:209], v[92:95]
	v_mfma_f32_16x16x32_bf16 v[88:91], v[154:157], v[206:209], v[88:91]
	v_mfma_f32_16x16x32_bf16 v[76:79], v[146:149], v[214:217], v[76:79]
	v_mfma_f32_16x16x32_bf16 v[72:75], v[154:157], v[214:217], v[72:75]
	v_mfma_f32_16x16x32_bf16 v[116:119], v[158:161], v[180:183], v[116:119]
	v_mfma_f32_16x16x32_bf16 v[112:115], v[172:175], v[180:183], v[112:115]
	v_mfma_f32_16x16x32_bf16 v[100:103], v[158:161], v[188:191], v[100:103]
	v_mfma_f32_16x16x32_bf16 v[96:99], v[172:175], v[188:191], v[96:99]
	v_mfma_f32_16x16x32_bf16 v[84:87], v[158:161], v[202:205], v[84:87]
	v_mfma_f32_16x16x32_bf16 v[80:83], v[172:175], v[202:205], v[80:83]
	v_mfma_f32_16x16x32_bf16 v[68:71], v[158:161], v[210:213], v[68:71]
	v_mfma_f32_16x16x32_bf16 v[64:67], v[172:175], v[210:213], v[64:67]
	v_mfma_f32_16x16x32_bf16 v[116:119], v[168:171], v[184:187], v[116:119]
	v_mfma_f32_16x16x32_bf16 v[112:115], v[176:179], v[184:187], v[112:115]
	v_mfma_f32_16x16x32_bf16 v[100:103], v[168:171], v[198:201], v[100:103]
	v_mfma_f32_16x16x32_bf16 v[96:99], v[176:179], v[198:201], v[96:99]
	v_mfma_f32_16x16x32_bf16 v[84:87], v[168:171], v[206:209], v[84:87]
	v_mfma_f32_16x16x32_bf16 v[80:83], v[176:179], v[206:209], v[80:83]
	v_mfma_f32_16x16x32_bf16 v[68:71], v[168:171], v[214:217], v[68:71]
	v_mfma_f32_16x16x32_bf16 v[64:67], v[176:179], v[214:217], v[64:67]
	s_setprio 0
	s_barrier
; #define PG8_STAGE(bufoff, gbase, voff) do { _Pragma("unroll") for (int _i = 0; _i < 2; ++_i) \
;         __builtin_amdgcn_global_load_lds((const unsigned*)((const char*)(gbase) + (voff)[_i]), (PG8_LAS unsigned*)(lds + (bufoff) + ldsw + _i * 8192), 16, 0, 0); } while (0)
; #define PG8_LDA(dst, b, h) do { _Pragma("unroll") for (int m = 0; m < 4; ++m) _Pragma("unroll") for (int k = 0; k < 2; ++k) dst[m][k] = *(const PG8_LAS bf16x8*)(lds + PG8_SA(b, h) + aoff + m * 2048 + k * 1024); } while (0)
; #define PG8_MMA(ai, bj, At, Bt) do { __builtin_amdgcn_s_setprio(1); _Pragma("unroll") for (int m = 0; m < 4; ++m) _Pragma("unroll") for (int n = 0; n < 2; ++n) _Pragma("unroll") for (int k = 0; k < 2; ++k) \
;         acc[ai][bj][m][n] = __builtin_amdgcn_mfma_f32_16x16x32_bf16(Bt[n][k], At[m][k], acc[ai][bj][m][n], 0, 0, 0); __builtin_amdgcn_s_setprio(0); } while (0)
; #define PG8_WAIT_V(n) asm volatile("s_waitcnt vmcnt(" #n ")" ::: "memory")
; #define PG8_WAIT_L(n) asm volatile("s_waitcnt lgkmcnt(" #n ")" ::: "memory")
; #define PG8_BAR __builtin_amdgcn_s_barrier()
; #define PG8_SCHED __builtin_amdgcn_sched_barrier(0)
; template <class Epi, class Sched, bool ALIGN_EPI = false, bool SP2 = false>
; __device__ __forceinline__ void gemm_phase(PG8_LAS unsigned char* lds, const Gemm g, const Sched& S, const Epi& E) {
;     ...
;             PG8_LDA(At, 1, 1); PG8_STAGE(PG8_SB(1, 0), b3, voffB); PG8_STAGE(PG8_SB(1, 1), b3 + hstepB, voffB); PG8_STAGE(PG8_SA(1, 0), a3, voffA);
;             PG8_WAIT_V(8); PG8_WAIT_L(0); PG8_BAR; PG8_MMA(1, 0, At, B0); PG8_MMA(1, 1, At, B1); PG8_BAR; PG8_SCHED;
;     ...
;         if constexpr (ALIGN_EPI) { if (wr == 0) PG8_BAR; }
	s_add_i32 s40, s77, s56
	v_lshl_add_u64 v[162:163], v[162:163], 0, s[28:29]
	s_mov_b32 m0, s40
	ds_read_b128 v[180:183], v167 offset:49152
	ds_read_b128 v[184:187], v167 offset:50176
	ds_read_b128 v[188:191], v167 offset:51200
	ds_read_b128 v[198:201], v167 offset:52224
	ds_read_b128 v[202:205], v167 offset:53248
	ds_read_b128 v[206:209], v167 offset:54272
	ds_read_b128 v[210:213], v167 offset:55296
	ds_read_b128 v[214:217], v167 offset:56320
	global_load_lds_dwordx4 v[162:163], off
	v_lshl_add_u64 v[162:163], v[218:219], 0, s[28:29]
	s_add_i32 m0, s40, 0x2000
	s_add_i32 s40, s81, s56
	global_load_lds_dwordx4 v[162:163], off
	v_lshl_add_u64 v[162:163], v[220:221], 0, s[28:29]
	s_mov_b32 m0, s40
	s_nop 0
	global_load_lds_dwordx4 v[162:163], off
	v_lshl_add_u64 v[162:163], v[222:223], 0, s[28:29]
	s_add_i32 m0, s40, 0x2000
	s_nop 0
	global_load_lds_dwordx4 v[162:163], off
	v_lshl_add_u64 v[162:163], v[224:225], 0, s[28:29]
	s_mov_b32 m0, s36
	s_nop 0
	global_load_lds_dwordx4 v[162:163], off
	v_lshl_add_u64 v[162:163], v[250:251], 0, s[28:29]
	s_mov_b32 m0, s37
	s_nop 0
	global_load_lds_dwordx4 v[162:163], off
	s_waitcnt vmcnt(8) lgkmcnt(0)
	s_barrier
	s_setprio 1
	v_mfma_f32_16x16x32_bf16 v[60:63], v[142:145], v[180:183], v[60:63]
	v_mfma_f32_16x16x32_bf16 v[56:59], v[150:153], v[180:183], v[56:59]
	v_mfma_f32_16x16x32_bf16 v[44:47], v[142:145], v[188:191], v[44:47]
	v_mfma_f32_16x16x32_bf16 v[40:43], v[150:153], v[188:191], v[40:43]
	v_mfma_f32_16x16x32_bf16 v[28:31], v[142:145], v[202:205], v[28:31]
	v_mfma_f32_16x16x32_bf16 v[24:27], v[150:153], v[202:205], v[24:27]
	v_mfma_f32_16x16x32_bf16 v[12:15], v[142:145], v[210:213], v[12:15]
	v_mfma_f32_16x16x32_bf16 v[8:11], v[150:153], v[210:213], v[8:11]
	v_mfma_f32_16x16x32_bf16 v[60:63], v[146:149], v[184:187], v[60:63]
	v_mfma_f32_16x16x32_bf16 v[56:59], v[154:157], v[184:187], v[56:59]
	v_mfma_f32_16x16x32_bf16 v[44:47], v[146:149], v[198:201], v[44:47]
	v_mfma_f32_16x16x32_bf16 v[40:43], v[154:157], v[198:201], v[40:43]
	v_mfma_f32_16x16x32_bf16 v[28:31], v[146:149], v[206:209], v[28:31]
	v_mfma_f32_16x16x32_bf16 v[24:27], v[154:157], v[206:209], v[24:27]
	v_mfma_f32_16x16x32_bf16 v[12:15], v[146:149], v[214:217], v[12:15]
	v_mfma_f32_16x16x32_bf16 v[8:11], v[154:157], v[214:217], v[8:11]
	v_mfma_f32_16x16x32_bf16 v[52:55], v[158:161], v[180:183], v[52:55]
	v_mfma_f32_16x16x32_bf16 v[48:51], v[172:175], v[180:183], v[48:51]
	v_mfma_f32_16x16x32_bf16 v[36:39], v[158:161], v[188:191], v[36:39]
	v_mfma_f32_16x16x32_bf16 v[32:35], v[172:175], v[188:191], v[32:35]
	v_mfma_f32_16x16x32_bf16 v[20:23], v[158:161], v[202:205], v[20:23]
	v_mfma_f32_16x16x32_bf16 v[16:19], v[172:175], v[202:205], v[16:19]
	v_mfma_f32_16x16x32_bf16 v[4:7], v[158:161], v[210:213], v[4:7]
	v_mfma_f32_16x16x32_bf16 v[0:3], v[172:175], v[210:213], v[0:3]
	v_mfma_f32_16x16x32_bf16 v[52:55], v[168:171], v[184:187], v[52:55]
	v_mfma_f32_16x16x32_bf16 v[48:51], v[176:179], v[184:187], v[48:51]
	v_mfma_f32_16x16x32_bf16 v[36:39], v[168:171], v[198:201], v[36:39]
	v_mfma_f32_16x16x32_bf16 v[32:35], v[176:179], v[198:201], v[32:35]
	v_mfma_f32_16x16x32_bf16 v[20:23], v[168:171], v[206:209], v[20:23]
	v_mfma_f32_16x16x32_bf16 v[16:19], v[176:179], v[206:209], v[16:19]
	v_mfma_f32_16x16x32_bf16 v[4:7], v[168:171], v[214:217], v[4:7]
	v_mfma_f32_16x16x32_bf16 v[0:3], v[176:179], v[214:217], v[0:3]
	s_setprio 0
	s_barrier
	s_add_u32 vcc_lo, vcc_lo, 0x100
	s_addc_u32 vcc_hi, vcc_hi, 0
	s_add_u32 s44, s44, 0x100
	s_addc_u32 s45, s45, 0
	s_cmp_ge_u32 s76, s51
	s_mov_b32 s40, s76
	s_cbranch_scc0 .LBB0_460
	s_and_b64 vcc, exec, s[74:75]
	s_cbranch_vccz .LBB0_463
	s_barrier
